# main GEMM: first K-loop iteration of each tile peeled, accumulator init folded into the first MFMA per accumulator (SrcC=0); 64 zeroing moves per tile removed
# speedup vs baseline: 1.0099x; 1.0099x over previous
; #define LDA(dst, b, h) for (int m = 0; m < 4; ++m) for (int k = 0; k < 2; ++k) \
;     dst[m][k] = *reinterpret_cast<const bf16x8*>(SA(b, h) + lds_byte(wr * 64 + m * 16 + fr, k * 32 + fq * 8))
; #define LDB(dst, b, h) for (int n = 0; n < 2; ++n) for (int k = 0; k < 2; ++k) \
;     dst[n][k] = *reinterpret_cast<const bf16x8*>(SB(b, h) + lds_byte(wc * 32 + n * 16 + fr, k * 32 + fq * 8))
; #define MMA(ai, bj, At_, Bt_) do { __builtin_amdgcn_s_setprio(1); \
;     for (int m = 0; m < 4; ++m) for (int n = 0; n < 2; ++n) for (int k = 0; k < 2; ++k) \
;       acc[ai][bj][m][n] = __builtin_amdgcn_mfma_f32_16x16x32_bf16(Bt_[n][k], At_[m][k], acc[ai][bj][m][n], 0, 0, 0); \
;     __builtin_amdgcn_s_setprio(0); } while (0)
; #define WAIT_L(n) asm volatile("s_waitcnt lgkmcnt(" #n ")" ::: "memory")
; #define BAR __builtin_amdgcn_s_barrier()
; #define SCHED __builtin_amdgcn_sched_barrier(0)
; #define STG(P, PTR, LD, O0) do { const bf16_t* _g = (PTR); \
;     __builtin_amdgcn_global_load_lds((const unsigned*)(_g + O0), (lds_u32*)((P) + swave * 1024), 16, 0, 0); \
;     __builtin_amdgcn_global_load_lds((const unsigned*)(_g + (size_t)64 * (LD) + O0), (lds_u32*)((P) + swave * 1024 + 8192), 16, 0, 0); } while (0)
; #define WAIT_L(n) asm volatile("s_waitcnt lgkmcnt(" #n ")" ::: "memory")
; #define BAR __builtin_amdgcn_s_barrier()
; #define SCHED __builtin_amdgcn_sched_barrier(0)
; __device__ __forceinline__ void gemm_stream(int swave, const GemmJob& J, char* shm, int vb, int G) {
;     ...
;       const bool last = (t == nt - 2);
;       const bf16_t* xA = last ? nA : cA; const bf16_t* xA1 = last ? nA1 : cA1; const int k2 = last ? 0 : t + 2;
;       const bf16_t* b2 = last ? nB : cB + (size_t)(t + 2) * 64; const bf16_t* b3 = b2 + 64;
;       LDB(B0, 0, 0); SCHED; LDA(At, 0, 0); STGA(SA(1, 1), cA, cA1, t + 1, 1);
;       WAIT_L(8); BAR; WAIT_L(0); MMA(0, 0, At, B0); BAR; SCHED;
;       LDB(B1, 0, 1); STG(SB(0, 0), b2, ldb, offB0);
;       BAR; WAIT_L(0); MMA(0, 1, At, B1); BAR;
;       LDA(At, 0, 1); STGA(SA(0, 0), xA, xA1, k2, 0);
;       BAR; WAIT_L(0); MMA(1, 0, At, B0); BAR; SCHED;
;       STG(SB(0, 1), b2 + hB, ldb, offB0);
;     ...
;     for (int a_ = 0; a_ < 2; ++a_)
; #pragma unroll
;       for (int b_ = 0; b_ < 2; ++b_)
; #pragma unroll
;         for (int m = 0; m < 4; ++m)
; #pragma unroll
;           for (int n = 0; n < 2; ++n) acc[a_][b_][m][n] = (f32x4){0.f, 0.f, 0.f, 0.f};
.LBB0_728:
	s_add_u32 s20, s2, 0x100
	s_addc_u32 s21, s3, 0
	s_mov_b32 s2, 0
	s_mov_b32 s29, 2
	ds_read_b128 v[164:167], v139
	ds_read_b128 v[168:171], v139 offset:1024
	ds_read_b128 v[172:175], v139 offset:2048
	ds_read_b128 v[176:179], v139 offset:3072
	s_cmp_eq_u32 s49, s29
	s_cselect_b64 s[68:69], -1, 0
	s_and_b64 s[64:65], s[68:69], exec
	s_cselect_b32 s52, s10, s8
	s_cselect_b32 s64, s11, s9
	s_add_i32 s33, s2, 2
	s_and_b64 s[68:69], s[68:69], exec
	s_cselect_b32 s71, s15, s21
	s_cselect_b32 s70, s14, s20
	s_cselect_b32 s68, 0, s33
	s_cselect_b32 s65, s12, s16
	s_cselect_b32 s66, s13, s17
	s_or_b32 s2, s2, 1
	s_cmp_lt_u32 s2, s36
	s_cselect_b64 vcc, -1, 0
	s_and_b64 s[2:3], vcc, exec
	s_cselect_b32 s3, 0, s36
	s_cselect_b32 s2, s38, s37
	s_not_b32 s3, s3
	s_add_i32 s94, s3, s29
	s_and_b64 s[72:73], vcc, exec
	s_cselect_b32 s3, s9, s17
	s_cselect_b32 s69, s8, s16
	s_lshl_b64 s[72:73], s[94:95], 7
	s_add_u32 s69, s69, s72
	s_addc_u32 s74, s3, s73
	s_mov_b32 s3, s95
	s_lshl_b64 s[72:73], s[2:3], 8
	s_add_u32 s72, s69, s72
	v_cndmask_b32_e32 v2, v138, v0, vcc
	s_addc_u32 s73, s74, s73
	s_add_i32 m0, s42, 0xc000
	s_lshl_b64 s[2:3], s[2:3], 7
	v_lshlrev_b64 v[212:213], 1, v[2:3]
	s_add_u32 s2, s72, s2
	v_lshl_add_u64 v[214:215], s[72:73], 0, v[212:213]
	s_addc_u32 s3, s73, s3
	ds_read_b128 v[180:183], v144
	ds_read_b128 v[188:191], v145
	ds_read_b128 v[196:199], v159
	ds_read_b128 v[204:207], v160
	global_load_lds_dwordx4 v[214:215], off
	v_lshl_add_u64 v[212:213], s[2:3], 0, v[212:213]
	s_add_i32 m0, s42, 0xe000
	s_nop 0
	global_load_lds_dwordx4 v[212:213], off
	s_waitcnt lgkmcnt(4)
	s_barrier
	s_waitcnt lgkmcnt(0)
	v_mfma_f32_16x16x32_bf16 v[128:131], v[164:167], v[180:183], 0
	ds_read_b128 v[184:187], v144 offset:1024
	v_mfma_f32_16x16x32_bf16 v[124:127], v[172:175], v[180:183], 0
	ds_read_b128 v[192:195], v145 offset:1024
	v_mfma_f32_16x16x32_bf16 v[120:123], v[164:167], v[188:191], 0
	ds_read_b128 v[200:203], v159 offset:1024
	v_mfma_f32_16x16x32_bf16 v[116:119], v[172:175], v[188:191], 0
	ds_read_b128 v[208:211], v160 offset:1024
	v_mfma_f32_16x16x32_bf16 v[104:107], v[164:167], v[196:199], 0
	v_mfma_f32_16x16x32_bf16 v[100:103], v[172:175], v[196:199], 0
	v_mfma_f32_16x16x32_bf16 v[88:91], v[164:167], v[204:207], 0
	v_mfma_f32_16x16x32_bf16 v[84:87], v[172:175], v[204:207], 0
	s_waitcnt lgkmcnt(0)
	v_mfma_f32_16x16x32_bf16 v[128:131], v[168:171], v[184:187], v[128:131]
	v_mfma_f32_16x16x32_bf16 v[124:127], v[176:179], v[184:187], v[124:127]
	v_mfma_f32_16x16x32_bf16 v[120:123], v[168:171], v[192:195], v[120:123]
	v_mfma_f32_16x16x32_bf16 v[116:119], v[176:179], v[192:195], v[116:119]
	v_mfma_f32_16x16x32_bf16 v[104:107], v[168:171], v[200:203], v[104:107]
	v_mfma_f32_16x16x32_bf16 v[100:103], v[176:179], v[200:203], v[100:103]
	v_mfma_f32_16x16x32_bf16 v[88:91], v[168:171], v[208:211], v[88:91]
	v_mfma_f32_16x16x32_bf16 v[84:87], v[176:179], v[208:211], v[84:87]
	s_barrier
	s_add_u32 s2, s70, s0
	s_mov_b32 m0, s43
	v_lshl_add_u64 v[228:229], s[70:71], 0, v[136:137]
	s_addc_u32 s3, s71, s1
	ds_read_b128 v[212:215], v161
	ds_read_b128 v[216:219], v161 offset:1024
	ds_read_b128 v[220:223], v161 offset:2048
	ds_read_b128 v[224:227], v161 offset:3072
	global_load_lds_dwordx4 v[228:229], off
	v_lshl_add_u64 v[230:231], s[2:3], 0, v[136:137]
	s_mov_b32 m0, s44
	s_nop 0
	global_load_lds_dwordx4 v[230:231], off
	s_barrier
	s_waitcnt lgkmcnt(0)
	v_mfma_f32_16x16x32_bf16 v[112:115], v[212:215], v[180:183], 0
	v_mfma_f32_16x16x32_bf16 v[108:111], v[220:223], v[180:183], 0
	s_cmp_lt_u32 s68, s36
	s_cselect_b64 vcc, -1, 0
	v_mfma_f32_16x16x32_bf16 v[96:99], v[212:215], v[188:191], 0
	s_and_b64 s[70:71], vcc, exec
	s_cselect_b32 s70, s38, s37
	v_mfma_f32_16x16x32_bf16 v[92:95], v[220:223], v[188:191], 0
	s_sub_i32 s69, s68, s36
	s_min_u32 s94, s68, s69
	v_mfma_f32_16x16x32_bf16 v[80:83], v[212:215], v[196:199], 0
	s_and_b64 s[72:73], vcc, exec
	s_cselect_b32 s69, s64, s66
	v_mfma_f32_16x16x32_bf16 v[76:79], v[220:223], v[196:199], 0
	s_cselect_b32 s71, s52, s65
	s_lshl_b64 s[72:73], s[94:95], 7
	v_mfma_f32_16x16x32_bf16 v[72:75], v[212:215], v[204:207], 0
	v_cndmask_b32_e32 v2, v138, v0, vcc
	s_add_u32 s72, s71, s72
	v_mfma_f32_16x16x32_bf16 v[68:71], v[220:223], v[204:207], 0
	s_mov_b32 s71, s95
	v_mfma_f32_16x16x32_bf16 v[112:115], v[216:219], v[184:187], v[112:115]
	s_addc_u32 s73, s69, s73
	v_mfma_f32_16x16x32_bf16 v[108:111], v[224:227], v[184:187], v[108:111]
	v_lshlrev_b64 v[232:233], 1, v[2:3]
	v_mfma_f32_16x16x32_bf16 v[96:99], v[216:219], v[192:195], v[96:99]
	s_lshl_b64 s[70:71], s[70:71], 7
	v_mfma_f32_16x16x32_bf16 v[92:95], v[224:227], v[192:195], v[92:95]
	v_lshl_add_u64 v[234:235], s[72:73], 0, v[232:233]
	v_mfma_f32_16x16x32_bf16 v[80:83], v[216:219], v[200:203], v[80:83]
	s_add_u32 s72, s72, s70
	v_mfma_f32_16x16x32_bf16 v[76:79], v[224:227], v[200:203], v[76:79]
	s_mov_b32 m0, s42
	v_mfma_f32_16x16x32_bf16 v[72:75], v[216:219], v[208:211], v[72:75]
	s_addc_u32 s73, s73, s71
	v_mfma_f32_16x16x32_bf16 v[68:71], v[224:227], v[208:211], v[68:71]
	s_barrier
	ds_read_b128 v[180:183], v144 offset:16384
	ds_read_b128 v[188:191], v145 offset:16384
	ds_read_b128 v[196:199], v159 offset:16384
	ds_read_b128 v[204:207], v160 offset:16384
	global_load_lds_dwordx4 v[234:235], off
	v_lshl_add_u64 v[234:235], s[72:73], 0, v[232:233]
	s_mov_b32 m0, s39
	s_nop 0
	global_load_lds_dwordx4 v[234:235], off
	s_barrier
; #define LDA(dst, b, h) for (int m = 0; m < 4; ++m) for (int k = 0; k < 2; ++k) \
;     dst[m][k] = *reinterpret_cast<const bf16x8*>(SA(b, h) + lds_byte(wr * 64 + m * 16 + fr, k * 32 + fq * 8))
; #define LDB(dst, b, h) for (int n = 0; n < 2; ++n) for (int k = 0; k < 2; ++k) \
;     dst[n][k] = *reinterpret_cast<const bf16x8*>(SB(b, h) + lds_byte(wc * 32 + n * 16 + fr, k * 32 + fq * 8))
; #define MMA(ai, bj, At_, Bt_) do { __builtin_amdgcn_s_setprio(1); \
;     for (int m = 0; m < 4; ++m) for (int n = 0; n < 2; ++n) for (int k = 0; k < 2; ++k) \
;       acc[ai][bj][m][n] = __builtin_amdgcn_mfma_f32_16x16x32_bf16(Bt_[n][k], At_[m][k], acc[ai][bj][m][n], 0, 0, 0); \
;     __builtin_amdgcn_s_setprio(0); } while (0)
; #define WAIT_V(n) asm volatile("s_waitcnt vmcnt(" #n ")" ::: "memory")
; #define WAIT_L(n) asm volatile("s_waitcnt lgkmcnt(" #n ")" ::: "memory")
; #define BAR __builtin_amdgcn_s_barrier()
; #define SCHED __builtin_amdgcn_sched_barrier(0)
; #define STG(P, PTR, LD, O0) do { const bf16_t* _g = (PTR); \
;     __builtin_amdgcn_global_load_lds((const unsigned*)(_g + O0), (lds_u32*)((P) + swave * 1024), 16, 0, 0); \
;     __builtin_amdgcn_global_load_lds((const unsigned*)(_g + (size_t)64 * (LD) + O0), (lds_u32*)((P) + swave * 1024 + 8192), 16, 0, 0); } while (0)
; #define LDA(dst, b, h) for (int m = 0; m < 4; ++m) for (int k = 0; k < 2; ++k) \
;     dst[m][k] = *reinterpret_cast<const bf16x8*>(SA(b, h) + lds_byte(wr * 64 + m * 16 + fr, k * 32 + fq * 8))
; #define WAIT_V(n) asm volatile("s_waitcnt vmcnt(" #n ")" ::: "memory")
; #define WAIT_L(n) asm volatile("s_waitcnt lgkmcnt(" #n ")" ::: "memory")
; __device__ __forceinline__ void gemm_stream(int swave, const GemmJob& J, char* shm, int vb, int G) {
;     ...
;       LDA(At, 0, 1); STGA(SA(0, 0), xA, xA1, k2, 0);
;       BAR; WAIT_L(0); MMA(1, 0, At, B0); BAR; SCHED;
;       STG(SB(0, 1), b2 + hB, ldb, offB0);
;       WAIT_V(6); BAR; MMA(1, 1, At, B1); BAR;
;       LDB(B0, 1, 0); SCHED; LDA(At, 1, 0); STGA(SA(0, 1), xA, xA1, k2, 1);
;       WAIT_L(8); BAR; WAIT_L(0); MMA(0, 0, At, B0); BAR; SCHED;
;       LDB(B1, 1, 1); STG(SB(1, 0), b3, ldb, offB0);
;       BAR; WAIT_L(0); MMA(0, 1, At, B1); BAR;
;       LDA(At, 1, 1); STGA(SA(1, 0), xA, xA1, k2 + 1, 0);
;       BAR; WAIT_L(0); MMA(1, 0, At, B0); BAR; SCHED;
;       STG(SB(1, 1), b3 + hB, ldb, offB0);
;       WAIT_V(6); BAR; MMA(1, 1, At, B1); BAR;
	s_waitcnt lgkmcnt(0)
	v_mfma_f32_16x16x32_bf16 v[64:67], v[164:167], v[180:183], 0
	ds_read_b128 v[184:187], v144 offset:17408
	v_mfma_f32_16x16x32_bf16 v[60:63], v[172:175], v[180:183], 0
	ds_read_b128 v[192:195], v145 offset:17408
	v_mfma_f32_16x16x32_bf16 v[56:59], v[164:167], v[188:191], 0
	ds_read_b128 v[200:203], v159 offset:17408
	v_mfma_f32_16x16x32_bf16 v[52:55], v[172:175], v[188:191], 0
	ds_read_b128 v[208:211], v160 offset:17408
	v_mfma_f32_16x16x32_bf16 v[40:43], v[164:167], v[196:199], 0
	v_mfma_f32_16x16x32_bf16 v[36:39], v[172:175], v[196:199], 0
	v_mfma_f32_16x16x32_bf16 v[24:27], v[164:167], v[204:207], 0
	v_mfma_f32_16x16x32_bf16 v[20:23], v[172:175], v[204:207], 0
	s_waitcnt lgkmcnt(0)
	v_mfma_f32_16x16x32_bf16 v[64:67], v[168:171], v[184:187], v[64:67]
	v_mfma_f32_16x16x32_bf16 v[60:63], v[176:179], v[184:187], v[60:63]
	v_mfma_f32_16x16x32_bf16 v[56:59], v[168:171], v[192:195], v[56:59]
	v_mfma_f32_16x16x32_bf16 v[52:55], v[176:179], v[192:195], v[52:55]
	v_mfma_f32_16x16x32_bf16 v[40:43], v[168:171], v[200:203], v[40:43]
	v_mfma_f32_16x16x32_bf16 v[36:39], v[176:179], v[200:203], v[36:39]
	v_mfma_f32_16x16x32_bf16 v[24:27], v[168:171], v[208:211], v[24:27]
	v_mfma_f32_16x16x32_bf16 v[20:23], v[176:179], v[208:211], v[20:23]
	s_barrier
	s_add_u32 s2, s2, s0
	s_addc_u32 s3, s3, s1
	v_lshl_add_u64 v[234:235], s[2:3], 0, v[136:137]
	s_add_u32 s2, s2, s0
	s_mov_b32 m0, s45
	s_addc_u32 s3, s3, s1
	global_load_lds_dwordx4 v[234:235], off
	v_lshl_add_u64 v[236:237], s[2:3], 0, v[136:137]
	s_mov_b32 m0, s46
	s_nop 0
	global_load_lds_dwordx4 v[236:237], off
	s_waitcnt vmcnt(6)
	s_barrier
	v_mfma_f32_16x16x32_bf16 v[48:51], v[212:215], v[180:183], 0
	v_mfma_f32_16x16x32_bf16 v[44:47], v[220:223], v[180:183], 0
	v_mfma_f32_16x16x32_bf16 v[32:35], v[212:215], v[188:191], 0
	v_mfma_f32_16x16x32_bf16 v[28:31], v[220:223], v[188:191], 0
	v_mfma_f32_16x16x32_bf16 v[16:19], v[212:215], v[196:199], 0
	v_mfma_f32_16x16x32_bf16 v[12:15], v[220:223], v[196:199], 0
	v_mfma_f32_16x16x32_bf16 v[8:11], v[212:215], v[204:207], 0
	v_mfma_f32_16x16x32_bf16 v[4:7], v[220:223], v[204:207], 0
	v_mfma_f32_16x16x32_bf16 v[48:51], v[216:219], v[184:187], v[48:51]
	v_mfma_f32_16x16x32_bf16 v[44:47], v[224:227], v[184:187], v[44:47]
	v_mfma_f32_16x16x32_bf16 v[32:35], v[216:219], v[192:195], v[32:35]
	v_mfma_f32_16x16x32_bf16 v[28:31], v[224:227], v[192:195], v[28:31]
	v_mfma_f32_16x16x32_bf16 v[16:19], v[216:219], v[200:203], v[16:19]
	v_mfma_f32_16x16x32_bf16 v[12:15], v[224:227], v[200:203], v[12:15]
	v_mfma_f32_16x16x32_bf16 v[8:11], v[216:219], v[208:211], v[8:11]
	v_mfma_f32_16x16x32_bf16 v[4:7], v[224:227], v[208:211], v[4:7]
	s_barrier
	ds_read_b128 v[164:167], v162
	ds_read_b128 v[168:171], v162 offset:1024
	ds_read_b128 v[172:175], v162 offset:2048
	ds_read_b128 v[176:179], v162 offset:3072
	s_add_u32 s2, s72, s70
	s_addc_u32 s3, s73, s71
	v_lshl_add_u64 v[212:213], s[2:3], 0, v[232:233]
	s_add_u32 s2, s2, s70
	s_mov_b32 m0, s47
	s_addc_u32 s3, s3, s71
	ds_read_b128 v[180:183], v144 offset:32768
	ds_read_b128 v[188:191], v145 offset:32768
	ds_read_b128 v[196:199], v159 offset:32768
	ds_read_b128 v[204:207], v160 offset:32768
	global_load_lds_dwordx4 v[212:213], off
	v_lshl_add_u64 v[212:213], s[2:3], 0, v[232:233]
	s_mov_b32 m0, s48
	s_nop 0
	global_load_lds_dwordx4 v[212:213], off
	s_waitcnt lgkmcnt(4)
	s_barrier
	s_waitcnt lgkmcnt(0)
	v_mfma_f32_16x16x32_bf16 v[128:131], v[164:167], v[180:183], v[128:131]
	ds_read_b128 v[184:187], v144 offset:33792
	v_mfma_f32_16x16x32_bf16 v[124:127], v[172:175], v[180:183], v[124:127]
	ds_read_b128 v[192:195], v145 offset:33792
	v_mfma_f32_16x16x32_bf16 v[120:123], v[164:167], v[188:191], v[120:123]
	ds_read_b128 v[200:203], v159 offset:33792
	v_mfma_f32_16x16x32_bf16 v[116:119], v[172:175], v[188:191], v[116:119]
	ds_read_b128 v[208:211], v160 offset:33792
	v_mfma_f32_16x16x32_bf16 v[104:107], v[164:167], v[196:199], v[104:107]
	v_mfma_f32_16x16x32_bf16 v[100:103], v[172:175], v[196:199], v[100:103]
	v_mfma_f32_16x16x32_bf16 v[88:91], v[164:167], v[204:207], v[88:91]
	v_mfma_f32_16x16x32_bf16 v[84:87], v[172:175], v[204:207], v[84:87]
	s_waitcnt lgkmcnt(0)
	v_mfma_f32_16x16x32_bf16 v[128:131], v[168:171], v[184:187], v[128:131]
	v_mfma_f32_16x16x32_bf16 v[124:127], v[176:179], v[184:187], v[124:127]
	v_mfma_f32_16x16x32_bf16 v[120:123], v[168:171], v[192:195], v[120:123]
	v_mfma_f32_16x16x32_bf16 v[116:119], v[176:179], v[192:195], v[116:119]
	v_mfma_f32_16x16x32_bf16 v[104:107], v[168:171], v[200:203], v[104:107]
	v_mfma_f32_16x16x32_bf16 v[100:103], v[176:179], v[200:203], v[100:103]
	v_mfma_f32_16x16x32_bf16 v[88:91], v[168:171], v[208:211], v[88:91]
	v_mfma_f32_16x16x32_bf16 v[84:87], v[176:179], v[208:211], v[84:87]
	s_barrier
	v_lshl_add_u64 v[228:229], v[228:229], 0, s[22:23]
	s_add_i32 m0, s42, 0x18000
	ds_read_b128 v[212:215], v163
	ds_read_b128 v[216:219], v163 offset:1024
	ds_read_b128 v[220:223], v163 offset:2048
	ds_read_b128 v[224:227], v163 offset:3072
	global_load_lds_dwordx4 v[228:229], off
	v_lshl_add_u64 v[228:229], v[230:231], 0, s[22:23]
	s_add_i32 m0, s42, 0x1a000
	s_nop 0
	global_load_lds_dwordx4 v[228:229], off
	s_barrier
; #define LDA(dst, b, h) for (int m = 0; m < 4; ++m) for (int k = 0; k < 2; ++k) \
;     dst[m][k] = *reinterpret_cast<const bf16x8*>(SA(b, h) + lds_byte(wr * 64 + m * 16 + fr, k * 32 + fq * 8))
; #define MMA(ai, bj, At_, Bt_) do { __builtin_amdgcn_s_setprio(1); \
;     for (int m = 0; m < 4; ++m) for (int n = 0; n < 2; ++n) for (int k = 0; k < 2; ++k) \
;       acc[ai][bj][m][n] = __builtin_amdgcn_mfma_f32_16x16x32_bf16(Bt_[n][k], At_[m][k], acc[ai][bj][m][n], 0, 0, 0); \
;     __builtin_amdgcn_s_setprio(0); } while (0)
; #define WAIT_V(n) asm volatile("s_waitcnt vmcnt(" #n ")" ::: "memory")
; #define WAIT_L(n) asm volatile("s_waitcnt lgkmcnt(" #n ")" ::: "memory")
; #define BAR __builtin_amdgcn_s_barrier()
; #define SCHED __builtin_amdgcn_sched_barrier(0)
; #define STG(P, PTR, LD, O0) do { const bf16_t* _g = (PTR); \
;     __builtin_amdgcn_global_load_lds((const unsigned*)(_g + O0), (lds_u32*)((P) + swave * 1024), 16, 0, 0); \
;     __builtin_amdgcn_global_load_lds((const unsigned*)(_g + (size_t)64 * (LD) + O0), (lds_u32*)((P) + swave * 1024 + 8192), 16, 0, 0); } while (0)
; #define LDA(dst, b, h) for (int m = 0; m < 4; ++m) for (int k = 0; k < 2; ++k) \
;     dst[m][k] = *reinterpret_cast<const bf16x8*>(SA(b, h) + lds_byte(wr * 64 + m * 16 + fr, k * 32 + fq * 8))
; #define MMA(ai, bj, At_, Bt_) do { __builtin_amdgcn_s_setprio(1); \
;     for (int m = 0; m < 4; ++m) for (int n = 0; n < 2; ++n) for (int k = 0; k < 2; ++k) \
;       acc[ai][bj][m][n] = __builtin_amdgcn_mfma_f32_16x16x32_bf16(Bt_[n][k], At_[m][k], acc[ai][bj][m][n], 0, 0, 0); \
;     __builtin_amdgcn_s_setprio(0); } while (0)
; #define WAIT_V(n) asm volatile("s_waitcnt vmcnt(" #n ")" ::: "memory")
; #define WAIT_L(n) asm volatile("s_waitcnt lgkmcnt(" #n ")" ::: "memory")
; #define BAR __builtin_amdgcn_s_barrier()
; #define SCHED __builtin_amdgcn_sched_barrier(0)
; __device__ __forceinline__ void gemm_stream(int swave, const GemmJob& J, char* shm, int vb, int G) {
;     ...
;       BAR; WAIT_L(0); MMA(0, 1, At, B1); BAR;
;       LDA(At, 1, 1); STGA(SA(1, 0), xA, xA1, k2 + 1, 0);
;       BAR; WAIT_L(0); MMA(1, 0, At, B0); BAR; SCHED;
;       STG(SB(1, 1), b3 + hB, ldb, offB0);
;       WAIT_V(6); BAR; MMA(1, 1, At, B1); BAR;
;     }
	s_waitcnt lgkmcnt(0)
	v_mfma_f32_16x16x32_bf16 v[112:115], v[212:215], v[180:183], v[112:115]
	v_mfma_f32_16x16x32_bf16 v[108:111], v[220:223], v[180:183], v[108:111]
	s_or_b32 s68, s68, 1
	s_cmp_lt_u32 s68, s36
	v_mfma_f32_16x16x32_bf16 v[96:99], v[212:215], v[188:191], v[96:99]
	s_cselect_b64 vcc, -1, 0
	s_and_b64 s[2:3], vcc, exec
	v_mfma_f32_16x16x32_bf16 v[92:95], v[220:223], v[188:191], v[92:95]
	s_cselect_b32 s69, s38, s37
	s_sub_i32 s2, s68, s36
	v_mfma_f32_16x16x32_bf16 v[80:83], v[212:215], v[196:199], v[80:83]
	s_min_u32 s94, s68, s2
	s_and_b64 s[2:3], vcc, exec
	v_mfma_f32_16x16x32_bf16 v[76:79], v[220:223], v[196:199], v[76:79]
	s_cselect_b32 s64, s64, s66
	s_cselect_b32 s52, s52, s65
	v_mfma_f32_16x16x32_bf16 v[72:75], v[212:215], v[204:207], v[72:75]
	s_lshl_b64 s[2:3], s[94:95], 7
	v_cndmask_b32_e32 v2, v138, v0, vcc
	v_mfma_f32_16x16x32_bf16 v[68:71], v[220:223], v[204:207], v[68:71]
	s_add_u32 s2, s52, s2
	v_mfma_f32_16x16x32_bf16 v[112:115], v[216:219], v[184:187], v[112:115]
	s_addc_u32 s3, s64, s3
	v_mfma_f32_16x16x32_bf16 v[108:111], v[224:227], v[184:187], v[108:111]
	v_lshlrev_b64 v[228:229], 1, v[2:3]
	v_mfma_f32_16x16x32_bf16 v[96:99], v[216:219], v[192:195], v[96:99]
	s_lshl_b32 s52, s69, 7
	v_mfma_f32_16x16x32_bf16 v[92:95], v[224:227], v[192:195], v[92:95]
	v_lshl_add_u64 v[230:231], s[2:3], 0, v[228:229]
	v_mfma_f32_16x16x32_bf16 v[80:83], v[216:219], v[200:203], v[80:83]
	s_add_u32 s2, s2, s52
	v_mfma_f32_16x16x32_bf16 v[76:79], v[224:227], v[200:203], v[76:79]
	s_mov_b32 m0, s54
	v_mfma_f32_16x16x32_bf16 v[72:75], v[216:219], v[208:211], v[72:75]
	s_addc_u32 s3, s3, 0
	v_mfma_f32_16x16x32_bf16 v[68:71], v[224:227], v[208:211], v[68:71]
	s_barrier
	ds_read_b128 v[180:183], v144 offset:49152
	ds_read_b128 v[188:191], v145 offset:49152
	ds_read_b128 v[196:199], v159 offset:49152
	ds_read_b128 v[204:207], v160 offset:49152
	global_load_lds_dwordx4 v[230:231], off
	v_lshl_add_u64 v[228:229], s[2:3], 0, v[228:229]
	s_mov_b32 m0, s55
	s_nop 0
	global_load_lds_dwordx4 v[228:229], off
	s_barrier
	s_waitcnt lgkmcnt(0)
	v_mfma_f32_16x16x32_bf16 v[64:67], v[164:167], v[180:183], v[64:67]
	ds_read_b128 v[184:187], v144 offset:50176
	v_mfma_f32_16x16x32_bf16 v[60:63], v[172:175], v[180:183], v[60:63]
	ds_read_b128 v[192:195], v145 offset:50176
	v_mfma_f32_16x16x32_bf16 v[56:59], v[164:167], v[188:191], v[56:59]
	ds_read_b128 v[200:203], v159 offset:50176
	v_mfma_f32_16x16x32_bf16 v[52:55], v[172:175], v[188:191], v[52:55]
	ds_read_b128 v[208:211], v160 offset:50176
	v_mfma_f32_16x16x32_bf16 v[40:43], v[164:167], v[196:199], v[40:43]
	v_mfma_f32_16x16x32_bf16 v[36:39], v[172:175], v[196:199], v[36:39]
	v_mfma_f32_16x16x32_bf16 v[24:27], v[164:167], v[204:207], v[24:27]
	v_mfma_f32_16x16x32_bf16 v[20:23], v[172:175], v[204:207], v[20:23]
	s_waitcnt lgkmcnt(0)
	v_mfma_f32_16x16x32_bf16 v[64:67], v[168:171], v[184:187], v[64:67]
	v_mfma_f32_16x16x32_bf16 v[60:63], v[176:179], v[184:187], v[60:63]
	v_mfma_f32_16x16x32_bf16 v[56:59], v[168:171], v[192:195], v[56:59]
	v_mfma_f32_16x16x32_bf16 v[52:55], v[176:179], v[192:195], v[52:55]
	v_mfma_f32_16x16x32_bf16 v[40:43], v[168:171], v[200:203], v[40:43]
	v_mfma_f32_16x16x32_bf16 v[36:39], v[176:179], v[200:203], v[36:39]
	v_mfma_f32_16x16x32_bf16 v[24:27], v[168:171], v[208:211], v[24:27]
	v_mfma_f32_16x16x32_bf16 v[20:23], v[176:179], v[208:211], v[20:23]
	s_barrier
	v_lshl_add_u64 v[164:165], v[234:235], 0, s[22:23]
	s_add_i32 m0, s42, 0x1c000
	s_nop 0
	global_load_lds_dwordx4 v[164:165], off
	v_lshl_add_u64 v[164:165], v[236:237], 0, s[22:23]
	s_add_i32 m0, s42, 0x1e000
	s_nop 0
	global_load_lds_dwordx4 v[164:165], off
	s_waitcnt vmcnt(6)
	s_barrier
	v_mfma_f32_16x16x32_bf16 v[48:51], v[212:215], v[180:183], v[48:51]
	v_mfma_f32_16x16x32_bf16 v[44:47], v[220:223], v[180:183], v[44:47]
	s_add_i32 s29, s29, 2
	v_mfma_f32_16x16x32_bf16 v[32:35], v[212:215], v[188:191], v[32:35]
	s_add_u32 s20, s20, 0x100
	v_mfma_f32_16x16x32_bf16 v[28:31], v[220:223], v[188:191], v[28:31]
	s_addc_u32 s21, s21, 0
	v_mfma_f32_16x16x32_bf16 v[16:19], v[212:215], v[196:199], v[16:19]
	s_cmp_ge_u32 s33, s49
	v_mfma_f32_16x16x32_bf16 v[12:15], v[220:223], v[196:199], v[12:15]
	s_mov_b32 s2, s33
	v_mfma_f32_16x16x32_bf16 v[8:11], v[212:215], v[204:207], v[8:11]
	v_mfma_f32_16x16x32_bf16 v[4:7], v[220:223], v[204:207], v[4:7]
	v_mfma_f32_16x16x32_bf16 v[48:51], v[216:219], v[184:187], v[48:51]
	v_mfma_f32_16x16x32_bf16 v[44:47], v[224:227], v[184:187], v[44:47]
	v_mfma_f32_16x16x32_bf16 v[32:35], v[216:219], v[192:195], v[32:35]
	v_mfma_f32_16x16x32_bf16 v[28:31], v[224:227], v[192:195], v[28:31]
	v_mfma_f32_16x16x32_bf16 v[16:19], v[216:219], v[200:203], v[16:19]
	v_mfma_f32_16x16x32_bf16 v[12:15], v[224:227], v[200:203], v[12:15]
	v_mfma_f32_16x16x32_bf16 v[8:11], v[216:219], v[208:211], v[8:11]
	v_mfma_f32_16x16x32_bf16 v[4:7], v[224:227], v[208:211], v[4:7]
	s_barrier
	s_cbranch_scc0 .LBB0_729
	s_branch .Lgemm_epi
; #define LDA(dst, b, h) for (int m = 0; m < 4; ++m) for (int k = 0; k < 2; ++k) \
;     dst[m][k] = *reinterpret_cast<const bf16x8*>(SA(b, h) + lds_byte(wr * 64 + m * 16 + fr, k * 32 + fq * 8))
; #define LDB(dst, b, h) for (int n = 0; n < 2; ++n) for (int k = 0; k < 2; ++k) \
;     dst[n][k] = *reinterpret_cast<const bf16x8*>(SB(b, h) + lds_byte(wc * 32 + n * 16 + fr, k * 32 + fq * 8))
; #define MMA(ai, bj, At_, Bt_) do { __builtin_amdgcn_s_setprio(1); \
;     for (int m = 0; m < 4; ++m) for (int n = 0; n < 2; ++n) for (int k = 0; k < 2; ++k) \
;       acc[ai][bj][m][n] = __builtin_amdgcn_mfma_f32_16x16x32_bf16(Bt_[n][k], At_[m][k], acc[ai][bj][m][n], 0, 0, 0); \
;     __builtin_amdgcn_s_setprio(0); } while (0)
; #define WAIT_V(n) asm volatile("s_waitcnt vmcnt(" #n ")" ::: "memory")
; #define WAIT_L(n) asm volatile("s_waitcnt lgkmcnt(" #n ")" ::: "memory")
; #define BAR __builtin_amdgcn_s_barrier()
; #define SCHED __builtin_amdgcn_sched_barrier(0)
; #define STG(P, PTR, LD, O0) do { const bf16_t* _g = (PTR); \
;     __builtin_amdgcn_global_load_lds((const unsigned*)(_g + O0), (lds_u32*)((P) + swave * 1024), 16, 0, 0); \
;     __builtin_amdgcn_global_load_lds((const unsigned*)(_g + (size_t)64 * (LD) + O0), (lds_u32*)((P) + swave * 1024 + 8192), 16, 0, 0); } while (0)
; #define LDA(dst, b, h) for (int m = 0; m < 4; ++m) for (int k = 0; k < 2; ++k) \
;     dst[m][k] = *reinterpret_cast<const bf16x8*>(SA(b, h) + lds_byte(wr * 64 + m * 16 + fr, k * 32 + fq * 8))
; #define WAIT_V(n) asm volatile("s_waitcnt vmcnt(" #n ")" ::: "memory")
; __device__ __forceinline__ void gemm_stream(int swave, const GemmJob& J, char* shm, int vb, int G) {
;     ...
;     for (int t = 0; t < nt; t += 2) {
;       const bool last = (t == nt - 2);
;       const bf16_t* xA = last ? nA : cA; const bf16_t* xA1 = last ? nA1 : cA1; const int k2 = last ? 0 : t + 2;
;       const bf16_t* b2 = last ? nB : cB + (size_t)(t + 2) * 64; const bf16_t* b3 = b2 + 64;
;       LDB(B0, 0, 0); SCHED; LDA(At, 0, 0); STGA(SA(1, 1), cA, cA1, t + 1, 1);
;       WAIT_L(8); BAR; WAIT_L(0); MMA(0, 0, At, B0); BAR; SCHED;
;       LDB(B1, 0, 1); STG(SB(0, 0), b2, ldb, offB0);
;       BAR; WAIT_L(0); MMA(0, 1, At, B1); BAR;
;       LDA(At, 0, 1); STGA(SA(0, 0), xA, xA1, k2, 0);
;       BAR; WAIT_L(0); MMA(1, 0, At, B0); BAR; SCHED;
;       STG(SB(0, 1), b2 + hB, ldb, offB0);
;       WAIT_V(6); BAR; MMA(1, 1, At, B1); BAR;
.LBB0_729:
	ds_read_b128 v[164:167], v139
	ds_read_b128 v[168:171], v139 offset:1024
	ds_read_b128 v[172:175], v139 offset:2048
	ds_read_b128 v[176:179], v139 offset:3072
	s_cmp_eq_u32 s49, s29
	s_cselect_b64 s[68:69], -1, 0
	s_and_b64 s[64:65], s[68:69], exec
	s_cselect_b32 s52, s10, s8
	s_cselect_b32 s64, s11, s9
	s_add_i32 s33, s2, 2
	s_and_b64 s[68:69], s[68:69], exec
	s_cselect_b32 s71, s15, s21
	s_cselect_b32 s70, s14, s20
	s_cselect_b32 s68, 0, s33
	s_cselect_b32 s65, s12, s16
	s_cselect_b32 s66, s13, s17
	s_or_b32 s2, s2, 1
	s_cmp_lt_u32 s2, s36
	s_cselect_b64 vcc, -1, 0
	s_and_b64 s[2:3], vcc, exec
	s_cselect_b32 s3, 0, s36
	s_cselect_b32 s2, s38, s37
	s_not_b32 s3, s3
	s_add_i32 s94, s3, s29
	s_and_b64 s[72:73], vcc, exec
	s_cselect_b32 s3, s9, s17
	s_cselect_b32 s69, s8, s16
	s_lshl_b64 s[72:73], s[94:95], 7
	s_add_u32 s69, s69, s72
	s_addc_u32 s74, s3, s73
	s_mov_b32 s3, s95
	s_lshl_b64 s[72:73], s[2:3], 8
	s_add_u32 s72, s69, s72
	v_cndmask_b32_e32 v2, v138, v0, vcc
	s_addc_u32 s73, s74, s73
	s_add_i32 m0, s42, 0xc000
	s_lshl_b64 s[2:3], s[2:3], 7
	v_lshlrev_b64 v[212:213], 1, v[2:3]
	s_add_u32 s2, s72, s2
	v_lshl_add_u64 v[214:215], s[72:73], 0, v[212:213]
	s_addc_u32 s3, s73, s3
	ds_read_b128 v[180:183], v144
	ds_read_b128 v[188:191], v145
	ds_read_b128 v[196:199], v159
	ds_read_b128 v[204:207], v160
	global_load_lds_dwordx4 v[214:215], off
	v_lshl_add_u64 v[212:213], s[2:3], 0, v[212:213]
	s_add_i32 m0, s42, 0xe000
	s_nop 0
	global_load_lds_dwordx4 v[212:213], off
	s_waitcnt lgkmcnt(4)
	s_barrier
	s_waitcnt lgkmcnt(0)
	v_mfma_f32_16x16x32_bf16 v[128:131], v[164:167], v[180:183], v[128:131]
	ds_read_b128 v[184:187], v144 offset:1024
	v_mfma_f32_16x16x32_bf16 v[124:127], v[172:175], v[180:183], v[124:127]
	ds_read_b128 v[192:195], v145 offset:1024
	v_mfma_f32_16x16x32_bf16 v[120:123], v[164:167], v[188:191], v[120:123]
	ds_read_b128 v[200:203], v159 offset:1024
	v_mfma_f32_16x16x32_bf16 v[116:119], v[172:175], v[188:191], v[116:119]
	ds_read_b128 v[208:211], v160 offset:1024
	v_mfma_f32_16x16x32_bf16 v[104:107], v[164:167], v[196:199], v[104:107]
	v_mfma_f32_16x16x32_bf16 v[100:103], v[172:175], v[196:199], v[100:103]
	v_mfma_f32_16x16x32_bf16 v[88:91], v[164:167], v[204:207], v[88:91]
	v_mfma_f32_16x16x32_bf16 v[84:87], v[172:175], v[204:207], v[84:87]
	s_waitcnt lgkmcnt(0)
	v_mfma_f32_16x16x32_bf16 v[128:131], v[168:171], v[184:187], v[128:131]
	v_mfma_f32_16x16x32_bf16 v[124:127], v[176:179], v[184:187], v[124:127]
	v_mfma_f32_16x16x32_bf16 v[120:123], v[168:171], v[192:195], v[120:123]
	v_mfma_f32_16x16x32_bf16 v[116:119], v[176:179], v[192:195], v[116:119]
	v_mfma_f32_16x16x32_bf16 v[104:107], v[168:171], v[200:203], v[104:107]
	v_mfma_f32_16x16x32_bf16 v[100:103], v[176:179], v[200:203], v[100:103]
	v_mfma_f32_16x16x32_bf16 v[88:91], v[168:171], v[208:211], v[88:91]
	v_mfma_f32_16x16x32_bf16 v[84:87], v[176:179], v[208:211], v[84:87]
	s_barrier
	s_add_u32 s2, s70, s0
	s_mov_b32 m0, s43
	v_lshl_add_u64 v[228:229], s[70:71], 0, v[136:137]
	s_addc_u32 s3, s71, s1
	ds_read_b128 v[212:215], v161
	ds_read_b128 v[216:219], v161 offset:1024
	ds_read_b128 v[220:223], v161 offset:2048
	ds_read_b128 v[224:227], v161 offset:3072
	global_load_lds_dwordx4 v[228:229], off
	v_lshl_add_u64 v[230:231], s[2:3], 0, v[136:137]
	s_mov_b32 m0, s44
	s_nop 0
	global_load_lds_dwordx4 v[230:231], off
	s_barrier
	s_waitcnt lgkmcnt(0)
	v_mfma_f32_16x16x32_bf16 v[112:115], v[212:215], v[180:183], v[112:115]
	v_mfma_f32_16x16x32_bf16 v[108:111], v[220:223], v[180:183], v[108:111]
	s_cmp_lt_u32 s68, s36
	s_cselect_b64 vcc, -1, 0
	v_mfma_f32_16x16x32_bf16 v[96:99], v[212:215], v[188:191], v[96:99]
	s_and_b64 s[70:71], vcc, exec
	s_cselect_b32 s70, s38, s37
	v_mfma_f32_16x16x32_bf16 v[92:95], v[220:223], v[188:191], v[92:95]
	s_sub_i32 s69, s68, s36
	s_min_u32 s94, s68, s69
	v_mfma_f32_16x16x32_bf16 v[80:83], v[212:215], v[196:199], v[80:83]
	s_and_b64 s[72:73], vcc, exec
	s_cselect_b32 s69, s64, s66
	v_mfma_f32_16x16x32_bf16 v[76:79], v[220:223], v[196:199], v[76:79]
	s_cselect_b32 s71, s52, s65
	s_lshl_b64 s[72:73], s[94:95], 7
	v_mfma_f32_16x16x32_bf16 v[72:75], v[212:215], v[204:207], v[72:75]
	v_cndmask_b32_e32 v2, v138, v0, vcc
	s_add_u32 s72, s71, s72
	v_mfma_f32_16x16x32_bf16 v[68:71], v[220:223], v[204:207], v[68:71]
	s_mov_b32 s71, s95
	v_mfma_f32_16x16x32_bf16 v[112:115], v[216:219], v[184:187], v[112:115]
	s_addc_u32 s73, s69, s73
	v_mfma_f32_16x16x32_bf16 v[108:111], v[224:227], v[184:187], v[108:111]
	v_lshlrev_b64 v[232:233], 1, v[2:3]
	v_mfma_f32_16x16x32_bf16 v[96:99], v[216:219], v[192:195], v[96:99]
	s_lshl_b64 s[70:71], s[70:71], 7
	v_mfma_f32_16x16x32_bf16 v[92:95], v[224:227], v[192:195], v[92:95]
	v_lshl_add_u64 v[234:235], s[72:73], 0, v[232:233]
	v_mfma_f32_16x16x32_bf16 v[80:83], v[216:219], v[200:203], v[80:83]
	s_add_u32 s72, s72, s70
	v_mfma_f32_16x16x32_bf16 v[76:79], v[224:227], v[200:203], v[76:79]
	s_mov_b32 m0, s42
	v_mfma_f32_16x16x32_bf16 v[72:75], v[216:219], v[208:211], v[72:75]
	s_addc_u32 s73, s73, s71
	v_mfma_f32_16x16x32_bf16 v[68:71], v[224:227], v[208:211], v[68:71]
	s_barrier
	ds_read_b128 v[180:183], v144 offset:16384
	ds_read_b128 v[188:191], v145 offset:16384
	ds_read_b128 v[196:199], v159 offset:16384
	ds_read_b128 v[204:207], v160 offset:16384
	global_load_lds_dwordx4 v[234:235], off
	v_lshl_add_u64 v[234:235], s[72:73], 0, v[232:233]
	s_mov_b32 m0, s39
	s_nop 0
	global_load_lds_dwordx4 v[234:235], off
	s_barrier
; #define LDA(dst, b, h) for (int m = 0; m < 4; ++m) for (int k = 0; k < 2; ++k) \
;     dst[m][k] = *reinterpret_cast<const bf16x8*>(SA(b, h) + lds_byte(wr * 64 + m * 16 + fr, k * 32 + fq * 8))
; #define LDB(dst, b, h) for (int n = 0; n < 2; ++n) for (int k = 0; k < 2; ++k) \
;     dst[n][k] = *reinterpret_cast<const bf16x8*>(SB(b, h) + lds_byte(wc * 32 + n * 16 + fr, k * 32 + fq * 8))
; #define MMA(ai, bj, At_, Bt_) do { __builtin_amdgcn_s_setprio(1); \
;     for (int m = 0; m < 4; ++m) for (int n = 0; n < 2; ++n) for (int k = 0; k < 2; ++k) \
;       acc[ai][bj][m][n] = __builtin_amdgcn_mfma_f32_16x16x32_bf16(Bt_[n][k], At_[m][k], acc[ai][bj][m][n], 0, 0, 0); \
;     __builtin_amdgcn_s_setprio(0); } while (0)
; #define WAIT_V(n) asm volatile("s_waitcnt vmcnt(" #n ")" ::: "memory")
; #define WAIT_L(n) asm volatile("s_waitcnt lgkmcnt(" #n ")" ::: "memory")
; #define BAR __builtin_amdgcn_s_barrier()
; #define SCHED __builtin_amdgcn_sched_barrier(0)
; #define STG(P, PTR, LD, O0) do { const bf16_t* _g = (PTR); \
;     __builtin_amdgcn_global_load_lds((const unsigned*)(_g + O0), (lds_u32*)((P) + swave * 1024), 16, 0, 0); \
;     __builtin_amdgcn_global_load_lds((const unsigned*)(_g + (size_t)64 * (LD) + O0), (lds_u32*)((P) + swave * 1024 + 8192), 16, 0, 0); } while (0)
; #define LDA(dst, b, h) for (int m = 0; m < 4; ++m) for (int k = 0; k < 2; ++k) \
;     dst[m][k] = *reinterpret_cast<const bf16x8*>(SA(b, h) + lds_byte(wr * 64 + m * 16 + fr, k * 32 + fq * 8))
; #define LDB(dst, b, h) for (int n = 0; n < 2; ++n) for (int k = 0; k < 2; ++k) \
;     dst[n][k] = *reinterpret_cast<const bf16x8*>(SB(b, h) + lds_byte(wc * 32 + n * 16 + fr, k * 32 + fq * 8))
; #define WAIT_V(n) asm volatile("s_waitcnt vmcnt(" #n ")" ::: "memory")
; __device__ __forceinline__ void gemm_stream(int swave, const GemmJob& J, char* shm, int vb, int G) {
;     ...
;       LDA(At, 0, 1); STGA(SA(0, 0), xA, xA1, k2, 0);
;       BAR; WAIT_L(0); MMA(1, 0, At, B0); BAR; SCHED;
;       STG(SB(0, 1), b2 + hB, ldb, offB0);
;       WAIT_V(6); BAR; MMA(1, 1, At, B1); BAR;
;       LDB(B0, 1, 0); SCHED; LDA(At, 1, 0); STGA(SA(0, 1), xA, xA1, k2, 1);
;       WAIT_L(8); BAR; WAIT_L(0); MMA(0, 0, At, B0); BAR; SCHED;
;       LDB(B1, 1, 1); STG(SB(1, 0), b3, ldb, offB0);
;       BAR; WAIT_L(0); MMA(0, 1, At, B1); BAR;
;       LDA(At, 1, 1); STGA(SA(1, 0), xA, xA1, k2 + 1, 0);
	s_waitcnt lgkmcnt(0)
	v_mfma_f32_16x16x32_bf16 v[64:67], v[164:167], v[180:183], v[64:67]
	ds_read_b128 v[184:187], v144 offset:17408
	v_mfma_f32_16x16x32_bf16 v[60:63], v[172:175], v[180:183], v[60:63]
	ds_read_b128 v[192:195], v145 offset:17408
	v_mfma_f32_16x16x32_bf16 v[56:59], v[164:167], v[188:191], v[56:59]
	ds_read_b128 v[200:203], v159 offset:17408
	v_mfma_f32_16x16x32_bf16 v[52:55], v[172:175], v[188:191], v[52:55]
	ds_read_b128 v[208:211], v160 offset:17408
	v_mfma_f32_16x16x32_bf16 v[40:43], v[164:167], v[196:199], v[40:43]
	v_mfma_f32_16x16x32_bf16 v[36:39], v[172:175], v[196:199], v[36:39]
	v_mfma_f32_16x16x32_bf16 v[24:27], v[164:167], v[204:207], v[24:27]
	v_mfma_f32_16x16x32_bf16 v[20:23], v[172:175], v[204:207], v[20:23]
	s_waitcnt lgkmcnt(0)
	v_mfma_f32_16x16x32_bf16 v[64:67], v[168:171], v[184:187], v[64:67]
	v_mfma_f32_16x16x32_bf16 v[60:63], v[176:179], v[184:187], v[60:63]
	v_mfma_f32_16x16x32_bf16 v[56:59], v[168:171], v[192:195], v[56:59]
	v_mfma_f32_16x16x32_bf16 v[52:55], v[176:179], v[192:195], v[52:55]
	v_mfma_f32_16x16x32_bf16 v[40:43], v[168:171], v[200:203], v[40:43]
	v_mfma_f32_16x16x32_bf16 v[36:39], v[176:179], v[200:203], v[36:39]
	v_mfma_f32_16x16x32_bf16 v[24:27], v[168:171], v[208:211], v[24:27]
	v_mfma_f32_16x16x32_bf16 v[20:23], v[176:179], v[208:211], v[20:23]
	s_barrier
	s_add_u32 s2, s2, s0
	s_addc_u32 s3, s3, s1
	v_lshl_add_u64 v[234:235], s[2:3], 0, v[136:137]
	s_add_u32 s2, s2, s0
	s_mov_b32 m0, s45
	s_addc_u32 s3, s3, s1
	global_load_lds_dwordx4 v[234:235], off
	v_lshl_add_u64 v[236:237], s[2:3], 0, v[136:137]
	s_mov_b32 m0, s46
	s_nop 0
	global_load_lds_dwordx4 v[236:237], off
	s_waitcnt vmcnt(6)
	s_barrier
	v_mfma_f32_16x16x32_bf16 v[48:51], v[212:215], v[180:183], v[48:51]
	v_mfma_f32_16x16x32_bf16 v[44:47], v[220:223], v[180:183], v[44:47]
	v_mfma_f32_16x16x32_bf16 v[32:35], v[212:215], v[188:191], v[32:35]
	v_mfma_f32_16x16x32_bf16 v[28:31], v[220:223], v[188:191], v[28:31]
	v_mfma_f32_16x16x32_bf16 v[16:19], v[212:215], v[196:199], v[16:19]
	v_mfma_f32_16x16x32_bf16 v[12:15], v[220:223], v[196:199], v[12:15]
	v_mfma_f32_16x16x32_bf16 v[8:11], v[212:215], v[204:207], v[8:11]
	v_mfma_f32_16x16x32_bf16 v[4:7], v[220:223], v[204:207], v[4:7]
	v_mfma_f32_16x16x32_bf16 v[48:51], v[216:219], v[184:187], v[48:51]
	v_mfma_f32_16x16x32_bf16 v[44:47], v[224:227], v[184:187], v[44:47]
	v_mfma_f32_16x16x32_bf16 v[32:35], v[216:219], v[192:195], v[32:35]
	v_mfma_f32_16x16x32_bf16 v[28:31], v[224:227], v[192:195], v[28:31]
	v_mfma_f32_16x16x32_bf16 v[16:19], v[216:219], v[200:203], v[16:19]
	v_mfma_f32_16x16x32_bf16 v[12:15], v[224:227], v[200:203], v[12:15]
	v_mfma_f32_16x16x32_bf16 v[8:11], v[216:219], v[208:211], v[8:11]
	v_mfma_f32_16x16x32_bf16 v[4:7], v[224:227], v[208:211], v[4:7]
	s_barrier
	ds_read_b128 v[164:167], v162
	ds_read_b128 v[168:171], v162 offset:1024
	ds_read_b128 v[172:175], v162 offset:2048
	ds_read_b128 v[176:179], v162 offset:3072
	s_add_u32 s2, s72, s70
	s_addc_u32 s3, s73, s71
	v_lshl_add_u64 v[212:213], s[2:3], 0, v[232:233]
	s_add_u32 s2, s2, s70
	s_mov_b32 m0, s47
	s_addc_u32 s3, s3, s71
	ds_read_b128 v[180:183], v144 offset:32768
	ds_read_b128 v[188:191], v145 offset:32768
	ds_read_b128 v[196:199], v159 offset:32768
	ds_read_b128 v[204:207], v160 offset:32768
	global_load_lds_dwordx4 v[212:213], off
	v_lshl_add_u64 v[212:213], s[2:3], 0, v[232:233]
	s_mov_b32 m0, s48
	s_nop 0
	global_load_lds_dwordx4 v[212:213], off
	s_waitcnt lgkmcnt(4)
	s_barrier
	s_waitcnt lgkmcnt(0)
	v_mfma_f32_16x16x32_bf16 v[128:131], v[164:167], v[180:183], v[128:131]
	ds_read_b128 v[184:187], v144 offset:33792
	v_mfma_f32_16x16x32_bf16 v[124:127], v[172:175], v[180:183], v[124:127]
	ds_read_b128 v[192:195], v145 offset:33792
	v_mfma_f32_16x16x32_bf16 v[120:123], v[164:167], v[188:191], v[120:123]
	ds_read_b128 v[200:203], v159 offset:33792
	v_mfma_f32_16x16x32_bf16 v[116:119], v[172:175], v[188:191], v[116:119]
	ds_read_b128 v[208:211], v160 offset:33792
	v_mfma_f32_16x16x32_bf16 v[104:107], v[164:167], v[196:199], v[104:107]
	v_mfma_f32_16x16x32_bf16 v[100:103], v[172:175], v[196:199], v[100:103]
	v_mfma_f32_16x16x32_bf16 v[88:91], v[164:167], v[204:207], v[88:91]
	v_mfma_f32_16x16x32_bf16 v[84:87], v[172:175], v[204:207], v[84:87]
	s_waitcnt lgkmcnt(0)
	v_mfma_f32_16x16x32_bf16 v[128:131], v[168:171], v[184:187], v[128:131]
	v_mfma_f32_16x16x32_bf16 v[124:127], v[176:179], v[184:187], v[124:127]
	v_mfma_f32_16x16x32_bf16 v[120:123], v[168:171], v[192:195], v[120:123]
	v_mfma_f32_16x16x32_bf16 v[116:119], v[176:179], v[192:195], v[116:119]
	v_mfma_f32_16x16x32_bf16 v[104:107], v[168:171], v[200:203], v[104:107]
	v_mfma_f32_16x16x32_bf16 v[100:103], v[176:179], v[200:203], v[100:103]
	v_mfma_f32_16x16x32_bf16 v[88:91], v[168:171], v[208:211], v[88:91]
	v_mfma_f32_16x16x32_bf16 v[84:87], v[176:179], v[208:211], v[84:87]
	s_barrier
	v_lshl_add_u64 v[228:229], v[228:229], 0, s[22:23]
	s_add_i32 m0, s42, 0x18000
	ds_read_b128 v[212:215], v163
	ds_read_b128 v[216:219], v163 offset:1024
	ds_read_b128 v[220:223], v163 offset:2048
	ds_read_b128 v[224:227], v163 offset:3072
	global_load_lds_dwordx4 v[228:229], off
	v_lshl_add_u64 v[228:229], v[230:231], 0, s[22:23]
	s_add_i32 m0, s42, 0x1a000
	s_nop 0
	global_load_lds_dwordx4 v[228:229], off
	s_barrier
; #define LDA(dst, b, h) for (int m = 0; m < 4; ++m) for (int k = 0; k < 2; ++k) \
;     dst[m][k] = *reinterpret_cast<const bf16x8*>(SA(b, h) + lds_byte(wr * 64 + m * 16 + fr, k * 32 + fq * 8))
; #define MMA(ai, bj, At_, Bt_) do { __builtin_amdgcn_s_setprio(1); \
;     for (int m = 0; m < 4; ++m) for (int n = 0; n < 2; ++n) for (int k = 0; k < 2; ++k) \
;       acc[ai][bj][m][n] = __builtin_amdgcn_mfma_f32_16x16x32_bf16(Bt_[n][k], At_[m][k], acc[ai][bj][m][n], 0, 0, 0); \
;     __builtin_amdgcn_s_setprio(0); } while (0)
; #define WAIT_V(n) asm volatile("s_waitcnt vmcnt(" #n ")" ::: "memory")
; #define WAIT_L(n) asm volatile("s_waitcnt lgkmcnt(" #n ")" ::: "memory")
; #define BAR __builtin_amdgcn_s_barrier()
; #define SCHED __builtin_amdgcn_sched_barrier(0)
; #define STG(P, PTR, LD, O0) do { const bf16_t* _g = (PTR); \
;     __builtin_amdgcn_global_load_lds((const unsigned*)(_g + O0), (lds_u32*)((P) + swave * 1024), 16, 0, 0); \
;     __builtin_amdgcn_global_load_lds((const unsigned*)(_g + (size_t)64 * (LD) + O0), (lds_u32*)((P) + swave * 1024 + 8192), 16, 0, 0); } while (0)
; #define LDA(dst, b, h) for (int m = 0; m < 4; ++m) for (int k = 0; k < 2; ++k) \
;     dst[m][k] = *reinterpret_cast<const bf16x8*>(SA(b, h) + lds_byte(wr * 64 + m * 16 + fr, k * 32 + fq * 8))
; #define MMA(ai, bj, At_, Bt_) do { __builtin_amdgcn_s_setprio(1); \
;     for (int m = 0; m < 4; ++m) for (int n = 0; n < 2; ++n) for (int k = 0; k < 2; ++k) \
;       acc[ai][bj][m][n] = __builtin_amdgcn_mfma_f32_16x16x32_bf16(Bt_[n][k], At_[m][k], acc[ai][bj][m][n], 0, 0, 0); \
;     __builtin_amdgcn_s_setprio(0); } while (0)
; #define WAIT_V(n) asm volatile("s_waitcnt vmcnt(" #n ")" ::: "memory")
; #define WAIT_L(n) asm volatile("s_waitcnt lgkmcnt(" #n ")" ::: "memory")
; #define BAR __builtin_amdgcn_s_barrier()
; #define SCHED __builtin_amdgcn_sched_barrier(0)
; __device__ __forceinline__ void gemm_stream(int swave, const GemmJob& J, char* shm, int vb, int G) {
;     ...
;       BAR; WAIT_L(0); MMA(0, 1, At, B1); BAR;
;       LDA(At, 1, 1); STGA(SA(1, 0), xA, xA1, k2 + 1, 0);
;       BAR; WAIT_L(0); MMA(1, 0, At, B0); BAR; SCHED;
;       STG(SB(1, 1), b3 + hB, ldb, offB0);
;       WAIT_V(6); BAR; MMA(1, 1, At, B1); BAR;
;     }
	s_waitcnt lgkmcnt(0)
	v_mfma_f32_16x16x32_bf16 v[112:115], v[212:215], v[180:183], v[112:115]
	v_mfma_f32_16x16x32_bf16 v[108:111], v[220:223], v[180:183], v[108:111]
	s_or_b32 s68, s68, 1
	s_cmp_lt_u32 s68, s36
	v_mfma_f32_16x16x32_bf16 v[96:99], v[212:215], v[188:191], v[96:99]
	s_cselect_b64 vcc, -1, 0
	s_and_b64 s[2:3], vcc, exec
	v_mfma_f32_16x16x32_bf16 v[92:95], v[220:223], v[188:191], v[92:95]
	s_cselect_b32 s69, s38, s37
	s_sub_i32 s2, s68, s36
	v_mfma_f32_16x16x32_bf16 v[80:83], v[212:215], v[196:199], v[80:83]
	s_min_u32 s94, s68, s2
	s_and_b64 s[2:3], vcc, exec
	v_mfma_f32_16x16x32_bf16 v[76:79], v[220:223], v[196:199], v[76:79]
	s_cselect_b32 s64, s64, s66
	s_cselect_b32 s52, s52, s65
	v_mfma_f32_16x16x32_bf16 v[72:75], v[212:215], v[204:207], v[72:75]
	s_lshl_b64 s[2:3], s[94:95], 7
	v_cndmask_b32_e32 v2, v138, v0, vcc
	v_mfma_f32_16x16x32_bf16 v[68:71], v[220:223], v[204:207], v[68:71]
	s_add_u32 s2, s52, s2
	v_mfma_f32_16x16x32_bf16 v[112:115], v[216:219], v[184:187], v[112:115]
	s_addc_u32 s3, s64, s3
	v_mfma_f32_16x16x32_bf16 v[108:111], v[224:227], v[184:187], v[108:111]
	v_lshlrev_b64 v[228:229], 1, v[2:3]
	v_mfma_f32_16x16x32_bf16 v[96:99], v[216:219], v[192:195], v[96:99]
	s_lshl_b32 s52, s69, 7
	v_mfma_f32_16x16x32_bf16 v[92:95], v[224:227], v[192:195], v[92:95]
	v_lshl_add_u64 v[230:231], s[2:3], 0, v[228:229]
	v_mfma_f32_16x16x32_bf16 v[80:83], v[216:219], v[200:203], v[80:83]
	s_add_u32 s2, s2, s52
	v_mfma_f32_16x16x32_bf16 v[76:79], v[224:227], v[200:203], v[76:79]
	s_mov_b32 m0, s54
	v_mfma_f32_16x16x32_bf16 v[72:75], v[216:219], v[208:211], v[72:75]
	s_addc_u32 s3, s3, 0
	v_mfma_f32_16x16x32_bf16 v[68:71], v[224:227], v[208:211], v[68:71]
	s_barrier
	ds_read_b128 v[180:183], v144 offset:49152
	ds_read_b128 v[188:191], v145 offset:49152
	ds_read_b128 v[196:199], v159 offset:49152
	ds_read_b128 v[204:207], v160 offset:49152
	global_load_lds_dwordx4 v[230:231], off
	v_lshl_add_u64 v[228:229], s[2:3], 0, v[228:229]
	s_mov_b32 m0, s55
	s_nop 0
	global_load_lds_dwordx4 v[228:229], off
	s_barrier
	s_waitcnt lgkmcnt(0)
	v_mfma_f32_16x16x32_bf16 v[64:67], v[164:167], v[180:183], v[64:67]
	ds_read_b128 v[184:187], v144 offset:50176
	v_mfma_f32_16x16x32_bf16 v[60:63], v[172:175], v[180:183], v[60:63]
	ds_read_b128 v[192:195], v145 offset:50176
	v_mfma_f32_16x16x32_bf16 v[56:59], v[164:167], v[188:191], v[56:59]
	ds_read_b128 v[200:203], v159 offset:50176
	v_mfma_f32_16x16x32_bf16 v[52:55], v[172:175], v[188:191], v[52:55]
	ds_read_b128 v[208:211], v160 offset:50176
	v_mfma_f32_16x16x32_bf16 v[40:43], v[164:167], v[196:199], v[40:43]
	v_mfma_f32_16x16x32_bf16 v[36:39], v[172:175], v[196:199], v[36:39]
	v_mfma_f32_16x16x32_bf16 v[24:27], v[164:167], v[204:207], v[24:27]
	v_mfma_f32_16x16x32_bf16 v[20:23], v[172:175], v[204:207], v[20:23]
	s_waitcnt lgkmcnt(0)
	v_mfma_f32_16x16x32_bf16 v[64:67], v[168:171], v[184:187], v[64:67]
	v_mfma_f32_16x16x32_bf16 v[60:63], v[176:179], v[184:187], v[60:63]
	v_mfma_f32_16x16x32_bf16 v[56:59], v[168:171], v[192:195], v[56:59]
	v_mfma_f32_16x16x32_bf16 v[52:55], v[176:179], v[192:195], v[52:55]
	v_mfma_f32_16x16x32_bf16 v[40:43], v[168:171], v[200:203], v[40:43]
	v_mfma_f32_16x16x32_bf16 v[36:39], v[176:179], v[200:203], v[36:39]
	v_mfma_f32_16x16x32_bf16 v[24:27], v[168:171], v[208:211], v[24:27]
	v_mfma_f32_16x16x32_bf16 v[20:23], v[176:179], v[208:211], v[20:23]
	s_barrier
	v_lshl_add_u64 v[164:165], v[234:235], 0, s[22:23]
	s_add_i32 m0, s42, 0x1c000
	s_nop 0
	global_load_lds_dwordx4 v[164:165], off
	v_lshl_add_u64 v[164:165], v[236:237], 0, s[22:23]
	s_add_i32 m0, s42, 0x1e000
	s_nop 0
	global_load_lds_dwordx4 v[164:165], off
	s_waitcnt vmcnt(6)
	s_barrier
	v_mfma_f32_16x16x32_bf16 v[48:51], v[212:215], v[180:183], v[48:51]
	v_mfma_f32_16x16x32_bf16 v[44:47], v[220:223], v[180:183], v[44:47]
	s_add_i32 s29, s29, 2
	v_mfma_f32_16x16x32_bf16 v[32:35], v[212:215], v[188:191], v[32:35]
	s_add_u32 s20, s20, 0x100
	v_mfma_f32_16x16x32_bf16 v[28:31], v[220:223], v[188:191], v[28:31]
	s_addc_u32 s21, s21, 0
	v_mfma_f32_16x16x32_bf16 v[16:19], v[212:215], v[196:199], v[16:19]
	s_cmp_ge_u32 s33, s49
	v_mfma_f32_16x16x32_bf16 v[12:15], v[220:223], v[196:199], v[12:15]
	s_mov_b32 s2, s33
	v_mfma_f32_16x16x32_bf16 v[8:11], v[212:215], v[204:207], v[8:11]
	v_mfma_f32_16x16x32_bf16 v[4:7], v[220:223], v[204:207], v[4:7]
	v_mfma_f32_16x16x32_bf16 v[48:51], v[216:219], v[184:187], v[48:51]
	v_mfma_f32_16x16x32_bf16 v[44:47], v[224:227], v[184:187], v[44:47]
	v_mfma_f32_16x16x32_bf16 v[32:35], v[216:219], v[192:195], v[32:35]
	v_mfma_f32_16x16x32_bf16 v[28:31], v[224:227], v[192:195], v[28:31]
	v_mfma_f32_16x16x32_bf16 v[16:19], v[216:219], v[200:203], v[16:19]
	v_mfma_f32_16x16x32_bf16 v[12:15], v[224:227], v[200:203], v[12:15]
	v_mfma_f32_16x16x32_bf16 v[8:11], v[216:219], v[208:211], v[8:11]
	v_mfma_f32_16x16x32_bf16 v[4:7], v[224:227], v[208:211], v[4:7]
	s_barrier
	s_cbranch_scc0 .LBB0_729
; __device__ __forceinline__ unsigned pk2(float lo, float hi) { f32x2_t v = {lo, hi}; bf16x2_t b = __builtin_convertvector(v, bf16x2_t); return __builtin_bit_cast(unsigned, b); }
; #define WAIT_V(n) asm volatile("s_waitcnt vmcnt(" #n ")" ::: "memory")
; #define BAR __builtin_amdgcn_s_barrier()
; #define WAIT_V(n) asm volatile("s_waitcnt vmcnt(" #n ")" ::: "memory")
; #define BAR __builtin_amdgcn_s_barrier()
; __device__ __forceinline__ void gemm_stream(int swave, const GemmJob& J, char* shm, int vb, int G) {
;     ...
;     {
;       bf16_t* C = (bf16_t*)((char*)J.c0 + (size_t)cg * J.strideC);
; #pragma unroll
;       for (int ai = 0; ai < 2; ++ai)
; #pragma unroll
;         for (int m = 0; m < 4; ++m)
; #pragma unroll
;           for (int bj = 0; bj < 2; ++bj) {
;             const f32x4 v0 = acc[ai][bj][m][0], v1 = acc[ai][bj][m][1];
;             uint4 o; o.x = pk2(v0[0], v0[1]); o.y = pk2(v0[2], v0[3]); o.z = pk2(v1[0], v1[1]); o.w = pk2(v1[2], v1[3]);
;             *(uint4*)(C + (size_t)(cbrow + ai * 128 + wr * 64 + m * 16 + fr) * J.ldc + cbcol + bj * 128 + wc * 32 + fq * 8) = o;
;           }
;     }
;     if (!has_next) break;
; #pragma unroll
;     for (int a_ = 0; a_ < 2; ++a_)
; #pragma unroll
;       for (int b_ = 0; b_ < 2; ++b_)
; #pragma unroll
;         for (int m = 0; m < 4; ++m)
; #pragma unroll
;           for (int n = 0; n < 2; ++n) acc[a_][b_][m][n] = (f32x4){0.f, 0.f, 0.f, 0.f};
;     id = nid; cg = ng; cbrow = nbrow; cbcol = nbcol; cA = nA; cA1 = nA1; cB = nB;
;   }
;   WAIT_V(0);
;   if (wr == 0) BAR;
;   BAR;
.Lgemm_epi:
	v_add_u32_e32 v164, s5, v1
	s_ashr_i32 s5, s4, 31
	s_lshl_b64 s[2:3], s[4:5], 1
	v_ashrrev_i32_e32 v2, 31, v164
	s_add_u32 s2, s50, s2
	v_cvt_pk_bf16_f32 v128, v128, v129
	v_cvt_pk_bf16_f32 v129, v130, v131
	v_cvt_pk_bf16_f32 v130, v124, v125
	v_mul_lo_u32 v2, v2, s18
	v_mad_u64_u32 v[124:125], s[4:5], v164, s18, 0
	s_addc_u32 s3, s51, s3
	v_add_u32_e32 v125, v125, v2
	v_lshl_add_u64 v[124:125], v[124:125], 1, s[2:3]
	v_mov_b32_e32 v141, v3
	v_lshl_add_u64 v[124:125], v[124:125], 0, v[140:141]
	v_mov_b32_e32 v143, v3
	v_lshl_add_u64 v[124:125], v[124:125], 0, v[142:143]
	s_lshl_b32 s2, s18, 5
	s_mov_b32 s3, 0
	s_mul_i32 s4, s18, 0xa0
	s_mov_b32 s5, 0
	v_cvt_pk_bf16_f32 v112, v112, v113
	v_cvt_pk_bf16_f32 v113, v114, v115
	v_cvt_pk_bf16_f32 v114, v108, v109
	v_cvt_pk_bf16_f32 v115, v110, v111
	global_store_dwordx4 v[124:125], v[112:115], off offset:256
	v_cvt_pk_bf16_f32 v131, v126, v127
	v_cvt_pk_bf16_f32 v96, v96, v97
	v_lshl_add_u64 v[112:113], v[124:125], 0, s[2:3]
	v_cvt_pk_bf16_f32 v97, v98, v99
	v_cvt_pk_bf16_f32 v98, v92, v93
	v_cvt_pk_bf16_f32 v99, v94, v95
	global_store_dwordx4 v[124:125], v[128:131], off
	global_store_dwordx4 v[112:113], v[96:99], off offset:256
	v_cvt_pk_bf16_f32 v108, v120, v121
	v_cvt_pk_bf16_f32 v109, v122, v123
	v_lshl_add_u64 v[96:97], v[112:113], 0, s[2:3]
	v_cvt_pk_bf16_f32 v110, v116, v117
	v_cvt_pk_bf16_f32 v111, v118, v119
	v_cvt_pk_bf16_f32 v80, v80, v81
	v_cvt_pk_bf16_f32 v81, v82, v83
	v_cvt_pk_bf16_f32 v82, v76, v77
	v_cvt_pk_bf16_f32 v83, v78, v79
	global_store_dwordx4 v[112:113], v[108:111], off
	global_store_dwordx4 v[96:97], v[80:83], off offset:256
	v_cvt_pk_bf16_f32 v64, v64, v65
	v_cvt_pk_bf16_f32 v65, v66, v67
	v_lshl_add_u64 v[80:81], v[96:97], 0, s[2:3]
	v_cvt_pk_bf16_f32 v66, v60, v61
	v_lshl_add_u64 v[60:61], v[80:81], 0, s[4:5]
	v_cvt_pk_bf16_f32 v72, v72, v73
	v_cvt_pk_bf16_f32 v73, v74, v75
	v_cvt_pk_bf16_f32 v74, v68, v69
	v_cvt_pk_bf16_f32 v67, v62, v63
	v_cvt_pk_bf16_f32 v92, v104, v105
	v_cvt_pk_bf16_f32 v93, v106, v107
	v_cvt_pk_bf16_f32 v94, v100, v101
	v_cvt_pk_bf16_f32 v95, v102, v103
	v_cvt_pk_bf16_f32 v76, v88, v89
	v_cvt_pk_bf16_f32 v77, v90, v91
	v_cvt_pk_bf16_f32 v78, v84, v85
	v_cvt_pk_bf16_f32 v79, v86, v87
	v_cvt_pk_bf16_f32 v75, v70, v71
	v_cvt_pk_bf16_f32 v48, v48, v49
	v_cvt_pk_bf16_f32 v49, v50, v51
	v_cvt_pk_bf16_f32 v50, v44, v45
	v_cvt_pk_bf16_f32 v51, v46, v47
	global_store_dwordx4 v[96:97], v[92:95], off
	global_store_dwordx4 v[80:81], v[76:79], off
	global_store_dwordx4 v[80:81], v[72:75], off offset:256
	global_store_dwordx4 v[60:61], v[48:51], off offset:256
	v_cvt_pk_bf16_f32 v32, v32, v33
	v_cvt_pk_bf16_f32 v33, v34, v35
	v_lshl_add_u64 v[48:49], v[60:61], 0, s[2:3]
	v_cvt_pk_bf16_f32 v34, v28, v29
	v_cvt_pk_bf16_f32 v35, v30, v31
	global_store_dwordx4 v[60:61], v[64:67], off
	global_store_dwordx4 v[48:49], v[32:35], off offset:256
	v_cvt_pk_bf16_f32 v44, v56, v57
	v_cvt_pk_bf16_f32 v45, v58, v59
	v_lshl_add_u64 v[32:33], v[48:49], 0, s[2:3]
	v_cvt_pk_bf16_f32 v46, v52, v53
	v_cvt_pk_bf16_f32 v47, v54, v55
	v_cvt_pk_bf16_f32 v16, v16, v17
	v_cvt_pk_bf16_f32 v17, v18, v19
	v_cvt_pk_bf16_f32 v18, v12, v13
	v_cvt_pk_bf16_f32 v19, v14, v15
	global_store_dwordx4 v[48:49], v[44:47], off
	global_store_dwordx4 v[32:33], v[16:19], off offset:256
	v_cvt_pk_bf16_f32 v28, v40, v41
	v_cvt_pk_bf16_f32 v29, v42, v43
	v_lshl_add_u64 v[16:17], v[32:33], 0, s[2:3]
	v_cvt_pk_bf16_f32 v30, v36, v37
	v_cvt_pk_bf16_f32 v31, v38, v39
	v_cvt_pk_bf16_f32 v12, v24, v25
	v_cvt_pk_bf16_f32 v13, v26, v27
	v_cvt_pk_bf16_f32 v14, v20, v21
	v_cvt_pk_bf16_f32 v15, v22, v23
	v_cvt_pk_bf16_f32 v8, v8, v9
	v_cvt_pk_bf16_f32 v9, v10, v11
	v_cvt_pk_bf16_f32 v10, v4, v5
	v_cvt_pk_bf16_f32 v11, v6, v7
	s_and_b64 vcc, exec, s[6:7]
	s_mov_b64 s[2:3], s[14:15]
	s_mov_b64 s[16:17], s[12:13]
	s_mov_b64 s[8:9], s[10:11]
	s_mov_b32 s4, s56
	s_mov_b32 s5, s28
	global_store_dwordx4 v[32:33], v[28:31], off
	global_store_dwordx4 v[16:17], v[12:15], off
	global_store_dwordx4 v[16:17], v[8:11], off offset:256
	s_cbranch_vccz .LBB0_726
	s_waitcnt vmcnt(0)
	s_movk_i32 s66, 0x100
	v_cmp_gt_u32_e32 vcc, s66, v135
	s_and_saveexec_b64 s[0:1], vcc
	s_cbranch_execz .LBB0_733
	s_barrier
